# gdn_intra step 0: per-head dt_bias/a_log fetched with scalar loads (no vmcnt(0) drain of the previous item's stores on the barrier-bounded path)
# speedup vs baseline: 1.0120x; 1.0036x over previous
; DI void gdn_intra(LAS unsigned char* lds, PP p, int l, int first, int stride) {
;     ...
;     if (tid < 64) {
;         const float bl = LG0, al = LG1;
;         const float beta = 1.f / (1.f + __expf(-bl));
;         const float xx = al + p->in[17][l * 8 + hd];
;         const float ex = __expf(fminf(xx, 20.f));
;         const float sp = xx > 20.f ? xx : (ex < 0.05f ? ex * (1.f - ex * (0.5f - ex * (0.33333333f - ex * 0.25f))) : __logf(1.f + ex));
;         float gc = -__expf(p->in[16][l * 8 + hd]) * sp;
.LBB0_421:
	v_mov_b32_e32 v138, v201
	s_ashr_i32 s55, s54, 31
	v_add_u32_e32 v0, 0x21000, v132
	v_add_u32_e32 v23, 0x20c00, v132
	v_add_u32_e32 v35, 0x20e00, v132
	v_lshl_add_u32 v1, v138, 2, v0
	v_add_u32_e32 v22, 0x20d00, v132
	v_add_u32_e32 v30, 0x20f00, v132
	v_cmp_gt_i32_e64 s[22:23], 64, v138
	s_waitcnt vmcnt(0)
	ds_write2st64_b32 v1, v133, v136 offset1:8
	ds_write_b32 v1, v137 offset:4096
	s_and_saveexec_b64 s[2:3], s[22:23]
	s_cbranch_execz .LBB0_430
	s_load_dwordx2 s[24:25], s[0:1], 0x88
	s_ashr_i32 s20, s54, 8
	s_add_i32 s20, s20, s65
	s_ashr_i32 s21, s20, 31
	s_lshl_b64 s[20:21], s[20:21], 2
	s_waitcnt lgkmcnt(0)
	s_add_u32 s24, s24, s20
	s_addc_u32 s25, s25, s21
	s_load_dword s26, s[24:25], 0x0
	s_waitcnt vmcnt(6) lgkmcnt(0)
	s_mov_b32 s24, 0x41a00000
	v_add_f32_e32 v1, s26, v134
	v_cmp_nlt_f32_e32 vcc, s24, v1
	s_and_saveexec_b64 s[26:27], vcc
	s_cbranch_execz .LBB0_428
	v_max_f32_e32 v1, v1, v1
	v_min_f32_e32 v1, 0x41a00000, v1
	v_mul_f32_e32 v1, 0x3fb8aa3b, v1
	v_exp_f32_e32 v2, v1
	s_mov_b32 s24, 0x3d4ccccd
	v_cmp_ngt_f32_e32 vcc, s24, v2
	s_and_saveexec_b64 s[24:25], vcc
	s_xor_b64 s[28:29], exec, s[24:25]
	s_cbranch_execz .LBB0_425
	v_add_f32_e32 v1, 1.0, v2
	v_cmp_gt_f32_e32 vcc, s10, v1
	s_mov_b32 s24, 0x3f317217
	s_nop 0
	v_cndmask_b32_e64 v2, 0, 32, vcc
	v_ldexp_f32 v1, v1, v2
	v_log_f32_e32 v1, v1
	s_nop 0
	v_mul_f32_e32 v2, 0x3f317217, v1
	v_fma_f32 v2, v1, s24, -v2
	v_fmac_f32_e32 v2, 0x3377d1cf, v1
	s_mov_b32 s24, 0x7f800000
	v_fmac_f32_e32 v2, 0x3f317217, v1
	v_cmp_lt_f32_e64 s[24:25], |v1|, s24
	s_nop 1
	v_cndmask_b32_e64 v1, v1, v2, s[24:25]
	v_mov_b32_e32 v2, 0x41b17218
	v_cndmask_b32_e32 v2, 0, v2, vcc
	v_sub_f32_e32 v1, v1, v2

; DI void gdn_intra(LAS unsigned char* lds, PP p, int l, int first, int stride) {
;     ...
;         const float beta = 1.f / (1.f + __expf(-bl));
;         const float xx = al + p->in[17][l * 8 + hd];
;         const float ex = __expf(fminf(xx, 20.f));
;         const float sp = xx > 20.f ? xx : (ex < 0.05f ? ex * (1.f - ex * (0.5f - ex * (0.33333333f - ex * 0.25f))) : __logf(1.f + ex));
;         float gc = -__expf(p->in[16][l * 8 + hd]) * sp;
; #pragma unroll
;         for (int off = 1; off < 64; off <<= 1) { const float t = __shfl_up(gc, off); if (tid >= off) gc += t; }
;         const float gl = __shfl(gc, 63);
;         scb[tid] = beta; scg[tid] = gc; sce[tid] = __expf(gc); scl[tid] = __expf(gl - gc);
;         if (tid == 0) ((float*)(p->ws + O_GL))[hd * 256 + n] = __expf(gl);
.LBB0_428:
	s_or_b64 exec, exec, s[26:27]
	v_mul_f32_e32 v2, 0xbfb8aa3b, v135
	v_exp_f32_e32 v2, v2
	s_nop 0
	v_add_f32_e32 v2, 1.0, v2
	v_rcp_f32_e32 v5, v2
	s_nop 0
	s_load_dwordx2 s[24:25], s[0:1], 0x80
	v_mul_f32_e32 v7, 1.0, v5
	v_fma_f32 v8, -v2, v7, 1.0
	v_fmac_f32_e32 v7, v8, v5
	s_waitcnt lgkmcnt(0)
	s_add_u32 s20, s24, s20
	s_addc_u32 s21, s25, s21
	v_div_fixup_f32 v2, v7, v2, 1.0
	s_load_dword s24, s[20:21], 0x0
	v_and_b32_e32 v6, 64, v220
	v_add_u32_e32 v7, -1, v220
	v_cmp_lt_i32_e32 vcc, v7, v6
	s_waitcnt lgkmcnt(0)
	v_mov_b32_e32 v4, s24
	v_mul_f32_e32 v4, 0x3fb8aa3b, v4
	v_exp_f32_e32 v4, v4
	v_cndmask_b32_e32 v7, v7, v220, vcc
	v_lshlrev_b32_e32 v7, 2, v7
	v_cmp_gt_i32_e32 vcc, 1, v138
	v_mul_f32_e64 v5, v1, -v4
	ds_bpermute_b32 v7, v7, v5
	s_waitcnt lgkmcnt(0)
	v_fma_f32 v1, v1, -v4, v7
	v_add_u32_e32 v4, -2, v220
	v_cndmask_b32_e32 v1, v1, v5, vcc
	v_cmp_lt_i32_e32 vcc, v4, v6
	v_lshlrev_b32_e32 v5, 2, v138
	s_nop 0
	v_cndmask_b32_e32 v4, v4, v220, vcc
	v_lshlrev_b32_e32 v4, 2, v4
	ds_bpermute_b32 v4, v4, v1
	v_cmp_gt_i32_e32 vcc, 2, v138
	s_waitcnt lgkmcnt(0)
	v_add_f32_e32 v4, v1, v4
	v_cndmask_b32_e32 v1, v4, v1, vcc
	v_add_u32_e32 v4, -4, v220
	v_cmp_lt_i32_e32 vcc, v4, v6
	s_nop 1
	v_cndmask_b32_e32 v4, v4, v220, vcc
	v_lshlrev_b32_e32 v4, 2, v4
	ds_bpermute_b32 v4, v4, v1
	v_cmp_gt_i32_e32 vcc, 4, v138
	s_waitcnt lgkmcnt(0)
	v_add_f32_e32 v4, v1, v4
	v_cndmask_b32_e32 v1, v4, v1, vcc
	v_add_u32_e32 v4, -8, v220
	v_cmp_lt_i32_e32 vcc, v4, v6
	s_nop 1
	v_cndmask_b32_e32 v4, v4, v220, vcc
	v_lshlrev_b32_e32 v4, 2, v4
	ds_bpermute_b32 v4, v4, v1
	v_cmp_gt_i32_e32 vcc, 8, v138
	s_waitcnt lgkmcnt(0)
	v_add_f32_e32 v4, v1, v4
	v_cndmask_b32_e32 v1, v4, v1, vcc
	v_add_u32_e32 v4, -16, v220
	v_cmp_lt_i32_e32 vcc, v4, v6
	s_nop 1
	v_cndmask_b32_e32 v4, v4, v220, vcc
	v_lshlrev_b32_e32 v4, 2, v4
	ds_bpermute_b32 v4, v4, v1
	v_cmp_gt_i32_e32 vcc, 16, v138
	s_waitcnt lgkmcnt(0)
	v_add_f32_e32 v4, v1, v4
	v_cndmask_b32_e32 v1, v4, v1, vcc
	v_subrev_u32_e32 v4, 32, v220
	v_cmp_lt_i32_e32 vcc, v4, v6
	v_add_u32_e32 v6, v23, v5
	ds_write_b32 v6, v2
	v_cndmask_b32_e32 v4, v4, v220, vcc
	v_lshlrev_b32_e32 v4, 2, v4
	ds_bpermute_b32 v4, v4, v1
	v_cmp_gt_i32_e32 vcc, 32, v138
	v_add_u32_e32 v2, v22, v5
	v_add_u32_e32 v6, v35, v5
	s_waitcnt lgkmcnt(0)
	v_add_f32_e32 v4, v1, v4
	v_cndmask_b32_e32 v4, v4, v1, vcc
	v_bfrev_b32_e32 v1, 0.5
	v_lshl_or_b32 v1, v220, 2, v1
	ds_bpermute_b32 v1, v1, v4
	ds_write_b32 v2, v4
	v_mul_f32_e32 v2, 0x3fb8aa3b, v4
	v_exp_f32_e32 v2, v2
	v_cmp_eq_u32_e32 vcc, 0, v138
	ds_write_b32 v6, v2
	s_waitcnt lgkmcnt(2)
	v_sub_f32_e32 v2, v1, v4
	v_mul_f32_e32 v2, 0x3fb8aa3b, v2
	v_exp_f32_e32 v2, v2
	v_add_u32_e32 v4, v30, v5
	ds_write_b32 v4, v2
	s_and_b64 exec, exec, vcc
	s_cbranch_execz .LBB0_430
	v_mul_f32_e32 v1, 0x3fb8aa3b, v1
	v_exp_f32_e32 v1, v1
	s_lshl_b64 s[20:21], s[54:55], 2
	s_add_u32 s20, s82, s20
	s_addc_u32 s21, s83, s21
	global_store_dword v3, v1, s[20:21]
